# w_in/GU epilogue stores sc1 nt (write-through streaming) instead of nt
# speedup vs baseline: 1.0049x; 1.0049x over previous
.LBB0_168:
	s_waitcnt vmcnt(8)
	v_pk_mul_f32 v[126:127], v[142:143], v[126:127] op_sel_hi:[0,1]
	v_pk_mul_f32 v[124:125], v[142:143], v[124:125] op_sel_hi:[0,1]
	v_pk_mul_f32 v[156:157], v[142:143], v[122:123] op_sel_hi:[0,1]
	v_pk_mul_f32 v[122:123], v[142:143], v[120:121] op_sel_hi:[0,1]
	v_cvt_pk_bf16_f32 v120, v124, v125
	v_cvt_pk_bf16_f32 v121, v126, v127
	v_cvt_pk_bf16_f32 v122, v122, v123
	v_cvt_pk_bf16_f32 v123, v156, v157
	ds_write_b128 v155, v[120:123]
	v_pk_mul_f32 v[118:119], v[142:143], v[118:119] op_sel_hi:[0,1]
	v_pk_mul_f32 v[116:117], v[142:143], v[116:117] op_sel_hi:[0,1]
	v_pk_mul_f32 v[120:121], v[142:143], v[114:115] op_sel_hi:[0,1]
	v_pk_mul_f32 v[114:115], v[142:143], v[112:113] op_sel_hi:[0,1]
	v_cvt_pk_bf16_f32 v112, v116, v117
	v_cvt_pk_bf16_f32 v113, v118, v119
	v_cvt_pk_bf16_f32 v114, v114, v115
	v_cvt_pk_bf16_f32 v115, v120, v121
	ds_write_b128 v155, v[112:115] offset:64
	v_add_u32_e32 v124, s3, v145
	v_mov_b64_e32 v[112:113], s[50:51]
	v_mad_i64_i32 v[122:123], s[38:39], v124, s6, v[112:113]
	s_lshl_b32 s38, s2, 8
	s_waitcnt lgkmcnt(0)
	s_ashr_i32 s39, s38, 31
	ds_read_b128 v[114:117], v158
	ds_read_b128 v[118:121], v158 offset:1152
	s_lshl_b64 s[38:39], s[38:39], 1
	v_lshl_add_u64 v[122:123], v[122:123], 0, s[38:39]
	v_lshl_add_u64 v[122:123], v[122:123], 0, s[0:1]
	v_lshl_add_u64 v[122:123], v[122:123], 0, v[208:209]
	s_movk_i32 s27, 0x7000
	s_waitcnt lgkmcnt(1)
	global_store_dwordx4 v[122:123], v[114:117], off sc1 nt
	v_pk_mul_f32 v[110:111], v[144:145], v[110:111] op_sel_hi:[0,1]
	v_pk_mul_f32 v[108:109], v[144:145], v[108:109] op_sel_hi:[0,1]
	v_add_co_u32_e32 v114, vcc, s27, v122
	v_pk_mul_f32 v[102:103], v[144:145], v[102:103] op_sel_hi:[0,1]
	s_nop 0
	v_addc_co_u32_e32 v115, vcc, 0, v123, vcc
	s_waitcnt lgkmcnt(0)
	global_store_dwordx4 v[114:115], v[118:121], off sc1 nt
	s_waitcnt lgkmcnt(0)
	v_pk_mul_f32 v[114:115], v[144:145], v[106:107] op_sel_hi:[0,1]
	v_pk_mul_f32 v[106:107], v[144:145], v[104:105] op_sel_hi:[0,1]
	v_cvt_pk_bf16_f32 v104, v108, v109
	v_cvt_pk_bf16_f32 v105, v110, v111
	v_cvt_pk_bf16_f32 v106, v106, v107
	v_cvt_pk_bf16_f32 v107, v114, v115
	ds_write_b128 v155, v[104:107]
	v_pk_mul_f32 v[104:105], v[144:145], v[98:99] op_sel_hi:[0,1]
	v_pk_mul_f32 v[98:99], v[144:145], v[96:97] op_sel_hi:[0,1]
	v_pk_mul_f32 v[100:101], v[144:145], v[100:101] op_sel_hi:[0,1]
	v_cvt_pk_bf16_f32 v96, v100, v101
	v_cvt_pk_bf16_f32 v97, v102, v103
	v_cvt_pk_bf16_f32 v98, v98, v99
	v_cvt_pk_bf16_f32 v99, v104, v105
	ds_write_b128 v155, v[96:99] offset:64
	s_waitcnt lgkmcnt(0)
	v_add_u32_e32 v104, s3, v147
	ds_read_b128 v[96:99], v158
	ds_read_b128 v[100:103], v158 offset:1152
	v_mad_i64_i32 v[104:105], s[40:41], v104, s6, v[112:113]
	v_lshl_add_u64 v[104:105], v[104:105], 0, s[38:39]
	v_lshl_add_u64 v[104:105], v[104:105], 0, s[0:1]
	v_lshl_add_u64 v[104:105], v[104:105], 0, v[208:209]
	s_waitcnt lgkmcnt(1)
	global_store_dwordx4 v[104:105], v[96:99], off sc1 nt
	v_pk_mul_f32 v[94:95], v[146:147], v[94:95] op_sel_hi:[0,1]
	v_pk_mul_f32 v[92:93], v[146:147], v[92:93] op_sel_hi:[0,1]
	v_add_co_u32_e32 v96, vcc, s27, v104
	v_pk_mul_f32 v[86:87], v[146:147], v[86:87] op_sel_hi:[0,1]
	s_nop 0
	v_addc_co_u32_e32 v97, vcc, 0, v105, vcc
	s_waitcnt lgkmcnt(0)
	global_store_dwordx4 v[96:97], v[100:103], off sc1 nt
	s_waitcnt lgkmcnt(0)
	v_pk_mul_f32 v[96:97], v[146:147], v[90:91] op_sel_hi:[0,1]
	v_pk_mul_f32 v[90:91], v[146:147], v[88:89] op_sel_hi:[0,1]
	v_cvt_pk_bf16_f32 v88, v92, v93
	v_cvt_pk_bf16_f32 v89, v94, v95
	v_cvt_pk_bf16_f32 v90, v90, v91
	v_cvt_pk_bf16_f32 v91, v96, v97
	ds_write_b128 v155, v[88:91]
	v_pk_mul_f32 v[88:89], v[146:147], v[82:83] op_sel_hi:[0,1]
	v_pk_mul_f32 v[82:83], v[146:147], v[80:81] op_sel_hi:[0,1]
	v_pk_mul_f32 v[84:85], v[146:147], v[84:85] op_sel_hi:[0,1]
	v_cvt_pk_bf16_f32 v80, v84, v85
	v_cvt_pk_bf16_f32 v81, v86, v87
	v_cvt_pk_bf16_f32 v82, v82, v83
	v_cvt_pk_bf16_f32 v83, v88, v89
	ds_write_b128 v155, v[80:83] offset:64
	s_waitcnt lgkmcnt(0)
	v_add_u32_e32 v88, s3, v149
	ds_read_b128 v[80:83], v158
	ds_read_b128 v[84:87], v158 offset:1152
	v_mad_i64_i32 v[88:89], s[40:41], v88, s6, v[112:113]
	v_lshl_add_u64 v[88:89], v[88:89], 0, s[38:39]
	v_lshl_add_u64 v[88:89], v[88:89], 0, s[0:1]
	v_lshl_add_u64 v[88:89], v[88:89], 0, v[208:209]
	s_waitcnt lgkmcnt(1)
	global_store_dwordx4 v[88:89], v[80:83], off sc1 nt
	v_pk_mul_f32 v[78:79], v[148:149], v[78:79] op_sel_hi:[0,1]
	v_pk_mul_f32 v[76:77], v[148:149], v[76:77] op_sel_hi:[0,1]
	v_add_co_u32_e32 v80, vcc, s27, v88
	v_pk_mul_f32 v[70:71], v[148:149], v[70:71] op_sel_hi:[0,1]
	s_nop 0
	v_addc_co_u32_e32 v81, vcc, 0, v89, vcc
	s_waitcnt lgkmcnt(0)
	global_store_dwordx4 v[80:81], v[84:87], off sc1 nt
	s_waitcnt lgkmcnt(0)
	v_pk_mul_f32 v[80:81], v[148:149], v[74:75] op_sel_hi:[0,1]
	v_pk_mul_f32 v[74:75], v[148:149], v[72:73] op_sel_hi:[0,1]
	v_cvt_pk_bf16_f32 v72, v76, v77
	v_cvt_pk_bf16_f32 v73, v78, v79
	v_cvt_pk_bf16_f32 v74, v74, v75
	v_cvt_pk_bf16_f32 v75, v80, v81
	ds_write_b128 v155, v[72:75]
	v_pk_mul_f32 v[72:73], v[148:149], v[66:67] op_sel_hi:[0,1]
	v_pk_mul_f32 v[66:67], v[148:149], v[64:65] op_sel_hi:[0,1]
	v_pk_mul_f32 v[68:69], v[148:149], v[68:69] op_sel_hi:[0,1]
	v_cvt_pk_bf16_f32 v64, v68, v69
	v_cvt_pk_bf16_f32 v65, v70, v71
	v_cvt_pk_bf16_f32 v66, v66, v67
	v_cvt_pk_bf16_f32 v67, v72, v73
	ds_write_b128 v155, v[64:67] offset:64
	s_waitcnt lgkmcnt(0)
	v_add_u32_e32 v72, s3, v151
	ds_read_b128 v[64:67], v158
	ds_read_b128 v[68:71], v158 offset:1152
	v_mad_i64_i32 v[72:73], s[2:3], v72, s6, v[112:113]
	v_lshl_add_u64 v[72:73], v[72:73], 0, s[38:39]
	v_lshl_add_u64 v[72:73], v[72:73], 0, s[0:1]
	v_lshl_add_u64 v[72:73], v[72:73], 0, v[208:209]
	s_waitcnt lgkmcnt(1)
	global_store_dwordx4 v[72:73], v[64:67], off sc1 nt
	v_pk_mul_f32 v[62:63], v[150:151], v[62:63] op_sel_hi:[0,1]
	v_pk_mul_f32 v[60:61], v[150:151], v[60:61] op_sel_hi:[0,1]
	v_add_co_u32_e32 v64, vcc, s27, v72
	v_pk_mul_f32 v[54:55], v[150:151], v[54:55] op_sel_hi:[0,1]
	s_nop 0
	v_addc_co_u32_e32 v65, vcc, 0, v73, vcc
	s_waitcnt lgkmcnt(0)
	global_store_dwordx4 v[64:65], v[68:71], off sc1 nt
	s_waitcnt lgkmcnt(0)
	v_pk_mul_f32 v[64:65], v[150:151], v[58:59] op_sel_hi:[0,1]
	v_pk_mul_f32 v[58:59], v[150:151], v[56:57] op_sel_hi:[0,1]
	v_cvt_pk_bf16_f32 v56, v60, v61
	v_cvt_pk_bf16_f32 v57, v62, v63
	v_cvt_pk_bf16_f32 v58, v58, v59
	v_cvt_pk_bf16_f32 v59, v64, v65
	ds_write_b128 v155, v[56:59]
	v_pk_mul_f32 v[56:57], v[150:151], v[50:51] op_sel_hi:[0,1]
	v_pk_mul_f32 v[50:51], v[150:151], v[48:49] op_sel_hi:[0,1]
	v_pk_mul_f32 v[52:53], v[150:151], v[52:53] op_sel_hi:[0,1]
	v_cvt_pk_bf16_f32 v48, v52, v53
	v_cvt_pk_bf16_f32 v49, v54, v55
	v_cvt_pk_bf16_f32 v50, v50, v51
	v_cvt_pk_bf16_f32 v51, v56, v57
	ds_write_b128 v155, v[48:51] offset:64
	s_waitcnt lgkmcnt(0)
	v_add_u32_e32 v56, 0x80, v124
	ds_read_b128 v[48:51], v158
	ds_read_b128 v[52:55], v158 offset:1152
	v_mad_i64_i32 v[56:57], s[2:3], v56, s6, v[112:113]
	v_lshl_add_u64 v[56:57], v[56:57], 0, s[38:39]
	v_lshl_add_u64 v[56:57], v[56:57], 0, s[0:1]
	v_lshl_add_u64 v[56:57], v[56:57], 0, v[208:209]
	s_waitcnt lgkmcnt(1)
	global_store_dwordx4 v[56:57], v[48:51], off sc1 nt
	v_pk_mul_f32 v[46:47], v[152:153], v[46:47] op_sel_hi:[0,1]
	v_pk_mul_f32 v[44:45], v[152:153], v[44:45] op_sel_hi:[0,1]
	v_add_co_u32_e32 v48, vcc, s27, v56
	v_pk_mul_f32 v[38:39], v[152:153], v[38:39] op_sel_hi:[0,1]
	s_nop 0
	v_addc_co_u32_e32 v49, vcc, 0, v57, vcc
	s_waitcnt lgkmcnt(0)
	global_store_dwordx4 v[48:49], v[52:55], off sc1 nt
	s_waitcnt lgkmcnt(0)
	v_pk_mul_f32 v[48:49], v[152:153], v[42:43] op_sel_hi:[0,1]
	v_pk_mul_f32 v[42:43], v[152:153], v[40:41] op_sel_hi:[0,1]
	v_cvt_pk_bf16_f32 v40, v44, v45
	v_cvt_pk_bf16_f32 v41, v46, v47
	v_cvt_pk_bf16_f32 v42, v42, v43
	v_cvt_pk_bf16_f32 v43, v48, v49
	ds_write_b128 v155, v[40:43]
	v_pk_mul_f32 v[40:41], v[152:153], v[34:35] op_sel_hi:[0,1]
	v_pk_mul_f32 v[34:35], v[152:153], v[32:33] op_sel_hi:[0,1]
	v_pk_mul_f32 v[36:37], v[152:153], v[36:37] op_sel_hi:[0,1]
	v_cvt_pk_bf16_f32 v32, v36, v37
	v_cvt_pk_bf16_f32 v33, v38, v39
	v_cvt_pk_bf16_f32 v34, v34, v35
	v_cvt_pk_bf16_f32 v35, v40, v41
	ds_write_b128 v155, v[32:35] offset:64
	s_waitcnt lgkmcnt(0)
	v_add_u32_e32 v40, 0x90, v124
	ds_read_b128 v[32:35], v158
	ds_read_b128 v[36:39], v158 offset:1152
	v_mad_i64_i32 v[40:41], s[2:3], v40, s6, v[112:113]
	v_lshl_add_u64 v[40:41], v[40:41], 0, s[38:39]
	v_lshl_add_u64 v[40:41], v[40:41], 0, s[0:1]
	v_lshl_add_u64 v[40:41], v[40:41], 0, v[208:209]
	s_waitcnt lgkmcnt(1)
	global_store_dwordx4 v[40:41], v[32:35], off sc1 nt
	v_pk_mul_f32 v[30:31], v[154:155], v[30:31] op_sel_hi:[0,1]
	v_pk_mul_f32 v[28:29], v[154:155], v[28:29] op_sel_hi:[0,1]
	v_add_co_u32_e32 v32, vcc, s27, v40
	v_pk_mul_f32 v[22:23], v[154:155], v[22:23] op_sel_hi:[0,1]
	s_nop 0
	v_addc_co_u32_e32 v33, vcc, 0, v41, vcc
	s_waitcnt lgkmcnt(0)
	global_store_dwordx4 v[32:33], v[36:39], off sc1 nt
	s_waitcnt lgkmcnt(0)
	v_pk_mul_f32 v[32:33], v[154:155], v[26:27] op_sel_hi:[0,1]
	v_pk_mul_f32 v[26:27], v[154:155], v[24:25] op_sel_hi:[0,1]
	v_cvt_pk_bf16_f32 v24, v28, v29
	v_cvt_pk_bf16_f32 v25, v30, v31
	v_cvt_pk_bf16_f32 v26, v26, v27
	v_cvt_pk_bf16_f32 v27, v32, v33
	ds_write_b128 v155, v[24:27]
	v_pk_mul_f32 v[24:25], v[154:155], v[18:19] op_sel_hi:[0,1]
	v_pk_mul_f32 v[18:19], v[154:155], v[16:17] op_sel_hi:[0,1]
	v_pk_mul_f32 v[20:21], v[154:155], v[20:21] op_sel_hi:[0,1]
	v_cvt_pk_bf16_f32 v16, v20, v21
	v_cvt_pk_bf16_f32 v17, v22, v23
	v_cvt_pk_bf16_f32 v18, v18, v19
	v_cvt_pk_bf16_f32 v19, v24, v25
	ds_write_b128 v155, v[16:19] offset:64
	s_waitcnt lgkmcnt(0)
	v_add_u32_e32 v24, 0xa0, v124
	ds_read_b128 v[16:19], v158
	ds_read_b128 v[20:23], v158 offset:1152
	v_mad_i64_i32 v[24:25], s[2:3], v24, s6, v[112:113]
	v_lshl_add_u64 v[24:25], v[24:25], 0, s[38:39]
	v_lshl_add_u64 v[24:25], v[24:25], 0, s[0:1]
	v_lshl_add_u64 v[24:25], v[24:25], 0, v[208:209]
	s_waitcnt lgkmcnt(1)
	global_store_dwordx4 v[24:25], v[16:19], off sc1 nt
	v_pk_mul_f32 v[14:15], v[140:141], v[14:15] op_sel_hi:[0,1]
	v_pk_mul_f32 v[12:13], v[140:141], v[12:13] op_sel_hi:[0,1]
	v_add_co_u32_e32 v16, vcc, s27, v24
	v_pk_mul_f32 v[6:7], v[140:141], v[6:7] op_sel_hi:[0,1]
	s_nop 0
	v_addc_co_u32_e32 v17, vcc, 0, v25, vcc
	s_waitcnt lgkmcnt(0)
	global_store_dwordx4 v[16:17], v[20:23], off sc1 nt
	s_waitcnt lgkmcnt(0)
	v_pk_mul_f32 v[16:17], v[140:141], v[10:11] op_sel_hi:[0,1]
	v_pk_mul_f32 v[10:11], v[140:141], v[8:9] op_sel_hi:[0,1]
	v_cvt_pk_bf16_f32 v8, v12, v13
	v_cvt_pk_bf16_f32 v9, v14, v15
	v_cvt_pk_bf16_f32 v10, v10, v11
	v_cvt_pk_bf16_f32 v11, v16, v17
	ds_write_b128 v155, v[8:11]
	v_pk_mul_f32 v[8:9], v[140:141], v[2:3] op_sel_hi:[0,1]
	v_pk_mul_f32 v[2:3], v[140:141], v[0:1] op_sel_hi:[0,1]
	v_pk_mul_f32 v[4:5], v[140:141], v[4:5] op_sel_hi:[0,1]
	v_cvt_pk_bf16_f32 v0, v4, v5
	v_cvt_pk_bf16_f32 v1, v6, v7
	v_cvt_pk_bf16_f32 v2, v2, v3
	v_cvt_pk_bf16_f32 v3, v8, v9
	ds_write_b128 v155, v[0:3] offset:64
	s_waitcnt lgkmcnt(0)
	v_add_u32_e32 v8, 0xb0, v124
	ds_read_b128 v[0:3], v158
	ds_read_b128 v[4:7], v158 offset:1152
	v_mad_i64_i32 v[8:9], s[2:3], v8, s6, v[112:113]
	v_lshl_add_u64 v[8:9], v[8:9], 0, s[38:39]
	v_lshl_add_u64 v[8:9], v[8:9], 0, s[0:1]
	v_lshl_add_u64 v[8:9], v[8:9], 0, v[208:209]
	s_waitcnt lgkmcnt(1)
	global_store_dwordx4 v[8:9], v[0:3], off sc1 nt
	s_movk_i32 s59, 0x7000
	s_mov_b64 s[2:3], -1
	v_add_co_u32_e32 v0, vcc, 0x7000, v8
	s_nop 1
	v_addc_co_u32_e32 v1, vcc, 0, v9, vcc
	s_waitcnt lgkmcnt(0)
	global_store_dwordx4 v[0:1], v[4:7], off sc1 nt
	s_waitcnt lgkmcnt(0)
	s_andn2_b64 vcc, exec, s[36:37]
	s_cbranch_vccnz .LBB0_159
	s_andn2_b64 vcc, exec, s[22:23]
	s_cbranch_vccnz .LBB0_158
	s_barrier
	s_branch .LBB0_158

.LBB0_576:
	s_waitcnt vmcnt(8)
	v_mul_f32_e32 v170, 0xbfb8aa3b, v168
	v_pk_mul_f32 v[176:177], v[170:171], v[116:117] op_sel_hi:[0,1]
	v_exp_f32_e32 v169, v176
	v_pk_mul_f32 v[120:121], v[124:125], v[120:121]
	v_pk_mul_f32 v[124:125], v[170:171], v[124:125] op_sel_hi:[0,1]
	v_pk_mul_f32 v[122:123], v[126:127], v[122:123]
	v_pk_mul_f32 v[174:175], v[170:171], v[118:119] op_sel_hi:[0,1]
	v_pk_mul_f32 v[126:127], v[170:171], v[126:127] op_sel_hi:[0,1]
	v_exp_f32_e32 v170, v124
	v_add_f32_e32 v124, 1.0, v169
	v_exp_f32_e32 v169, v177
	v_exp_f32_e32 v171, v125
	v_exp_f32_e32 v173, v126
	s_mul_i32 s3, s38, 22
	v_add_f32_e32 v125, 1.0, v169
	v_exp_f32_e32 v169, v174
	s_add_i32 s2, s3, s2
	s_ashr_i32 s3, s2, 31
	v_rcp_f32_e32 v124, v124
	v_add_f32_e32 v126, 1.0, v169
	v_exp_f32_e32 v169, v175
	v_exp_f32_e32 v175, v127
	v_add_f32_e32 v170, 1.0, v170
	v_rcp_f32_e32 v125, v125
	v_add_f32_e32 v127, 1.0, v169
	v_add_f32_e32 v171, 1.0, v171
	v_rcp_f32_e32 v126, v126
	v_rcp_f32_e32 v127, v127
	s_lshl_b64 s[2:3], s[2:3], 16
	v_rcp_f32_e32 v170, v170
	v_rcp_f32_e32 v171, v171
	v_add_f32_e32 v173, 1.0, v173
	v_add_f32_e32 v169, 1.0, v175
	s_add_u32 s38, s50, s2
	v_mul_f32_e32 v172, v168, v168
	v_rcp_f32_e32 v174, v173
	v_rcp_f32_e32 v175, v169
	v_pk_mul_f32 v[114:115], v[118:119], v[114:115]
	v_pk_mul_f32 v[112:113], v[116:117], v[112:113]
	s_addc_u32 s39, s51, s3
	v_pk_mul_f32 v[112:113], v[172:173], v[112:113] op_sel_hi:[0,1]
	v_pk_mul_f32 v[114:115], v[172:173], v[114:115] op_sel_hi:[0,1]
	v_lshl_add_u64 v[156:157], s[38:39], 0, v[136:137]
	v_pk_mul_f32 v[116:117], v[172:173], v[120:121] op_sel_hi:[0,1]
	v_pk_mul_f32 v[114:115], v[126:127], v[114:115]
	v_pk_mul_f32 v[112:113], v[124:125], v[112:113]
	v_lshl_add_u64 v[156:157], v[156:157], 0, v[208:209]
	v_pk_mul_f32 v[118:119], v[172:173], v[122:123] op_sel_hi:[0,1]
	v_pk_mul_f32 v[116:117], v[170:171], v[116:117]
	v_cvt_pk_bf16_f32 v112, v112, v113
	v_cvt_pk_bf16_f32 v113, v114, v115
	v_pk_mul_f32 v[118:119], v[174:175], v[118:119]
	v_cvt_pk_bf16_f32 v114, v116, v117
	v_pk_mul_f32 v[104:105], v[108:109], v[104:105]
	v_cvt_pk_bf16_f32 v115, v118, v119
	global_store_dwordx4 v[156:157], v[112:115], off sc1 nt
	v_pk_mul_f32 v[106:107], v[110:111], v[106:107]
	v_mul_f32_e32 v116, v167, v167
	v_mul_f32_e32 v114, 0xbfb8aa3b, v167
	v_pk_mul_f32 v[120:121], v[114:115], v[100:101] op_sel_hi:[0,1]
	v_pk_mul_f32 v[118:119], v[114:115], v[102:103] op_sel_hi:[0,1]
	v_exp_f32_e32 v115, v120
	v_exp_f32_e32 v118, v118
	v_exp_f32_e32 v119, v119
	v_pk_mul_f32 v[98:99], v[102:103], v[98:99]
	v_pk_mul_f32 v[108:109], v[114:115], v[108:109] op_sel_hi:[0,1]
	v_pk_mul_f32 v[110:111], v[114:115], v[110:111] op_sel_hi:[0,1]
	v_exp_f32_e32 v114, v108
	v_add_f32_e32 v108, 1.0, v115
	v_exp_f32_e32 v115, v121
	v_exp_f32_e32 v117, v109
	v_exp_f32_e32 v120, v111
	v_add_f32_e32 v111, 1.0, v119
	v_add_f32_e32 v109, 1.0, v115
	v_add_f32_e32 v115, 1.0, v117
	v_exp_f32_e32 v117, v110
	v_add_f32_e32 v110, 1.0, v118
	v_rcp_f32_e32 v108, v108
	v_add_f32_e32 v114, 1.0, v114
	v_rcp_f32_e32 v109, v109
	v_rcp_f32_e32 v110, v110
	v_add_f32_e32 v117, 1.0, v117
	v_rcp_f32_e32 v111, v111
	v_rcp_f32_e32 v114, v114
	v_rcp_f32_e32 v115, v115
	v_rcp_f32_e32 v118, v117
	v_add_f32_e32 v117, 1.0, v120
	v_rcp_f32_e32 v119, v117
	v_pk_mul_f32 v[96:97], v[100:101], v[96:97]
	v_pk_mul_f32 v[98:99], v[116:117], v[98:99] op_sel_hi:[0,1]
	v_pk_mul_f32 v[96:97], v[116:117], v[96:97] op_sel_hi:[0,1]
	v_lshl_add_u64 v[112:113], s[38:39], 0, v[138:139]
	v_pk_mul_f32 v[100:101], v[116:117], v[104:105] op_sel_hi:[0,1]
	v_pk_mul_f32 v[98:99], v[110:111], v[98:99]
	v_pk_mul_f32 v[96:97], v[108:109], v[96:97]
	v_lshl_add_u64 v[112:113], v[112:113], 0, v[208:209]
	v_pk_mul_f32 v[102:103], v[116:117], v[106:107] op_sel_hi:[0,1]
	v_pk_mul_f32 v[100:101], v[114:115], v[100:101]
	v_cvt_pk_bf16_f32 v96, v96, v97
	v_cvt_pk_bf16_f32 v97, v98, v99
	v_pk_mul_f32 v[102:103], v[118:119], v[102:103]
	v_cvt_pk_bf16_f32 v98, v100, v101
	v_pk_mul_f32 v[88:89], v[92:93], v[88:89]
	v_cvt_pk_bf16_f32 v99, v102, v103
	global_store_dwordx4 v[112:113], v[96:99], off sc1 nt
	v_pk_mul_f32 v[90:91], v[94:95], v[90:91]
	v_mul_f32_e32 v100, v166, v166
	v_mul_f32_e32 v98, 0xbfb8aa3b, v166
	v_pk_mul_f32 v[104:105], v[98:99], v[84:85] op_sel_hi:[0,1]
	v_pk_mul_f32 v[102:103], v[98:99], v[86:87] op_sel_hi:[0,1]
	v_exp_f32_e32 v99, v104
	v_exp_f32_e32 v102, v102
	v_exp_f32_e32 v103, v103
	v_pk_mul_f32 v[82:83], v[86:87], v[82:83]
	v_pk_mul_f32 v[92:93], v[98:99], v[92:93] op_sel_hi:[0,1]
	v_pk_mul_f32 v[94:95], v[98:99], v[94:95] op_sel_hi:[0,1]
	v_exp_f32_e32 v98, v92
	v_add_f32_e32 v92, 1.0, v99
	v_exp_f32_e32 v99, v105
	v_exp_f32_e32 v101, v93
	v_exp_f32_e32 v104, v95
	v_add_f32_e32 v95, 1.0, v103
	v_add_f32_e32 v93, 1.0, v99
	v_add_f32_e32 v99, 1.0, v101
	v_exp_f32_e32 v101, v94
	v_add_f32_e32 v94, 1.0, v102
	v_rcp_f32_e32 v92, v92
	v_add_f32_e32 v98, 1.0, v98
	v_rcp_f32_e32 v93, v93
	v_rcp_f32_e32 v94, v94
	v_add_f32_e32 v101, 1.0, v101
	v_rcp_f32_e32 v95, v95
	v_rcp_f32_e32 v98, v98
	v_rcp_f32_e32 v99, v99
	v_rcp_f32_e32 v102, v101
	v_add_f32_e32 v101, 1.0, v104
	v_rcp_f32_e32 v103, v101
	v_pk_mul_f32 v[80:81], v[84:85], v[80:81]
	v_pk_mul_f32 v[82:83], v[100:101], v[82:83] op_sel_hi:[0,1]
	v_pk_mul_f32 v[80:81], v[100:101], v[80:81] op_sel_hi:[0,1]
	v_lshl_add_u64 v[96:97], s[38:39], 0, v[140:141]
	v_pk_mul_f32 v[84:85], v[100:101], v[88:89] op_sel_hi:[0,1]
	v_pk_mul_f32 v[82:83], v[94:95], v[82:83]
	v_pk_mul_f32 v[80:81], v[92:93], v[80:81]
	v_lshl_add_u64 v[96:97], v[96:97], 0, v[208:209]
	v_pk_mul_f32 v[86:87], v[100:101], v[90:91] op_sel_hi:[0,1]
	v_pk_mul_f32 v[84:85], v[98:99], v[84:85]
	v_cvt_pk_bf16_f32 v80, v80, v81
	v_cvt_pk_bf16_f32 v81, v82, v83
	v_pk_mul_f32 v[86:87], v[102:103], v[86:87]
	v_cvt_pk_bf16_f32 v82, v84, v85
	v_pk_mul_f32 v[72:73], v[76:77], v[72:73]
	v_cvt_pk_bf16_f32 v83, v86, v87
	global_store_dwordx4 v[96:97], v[80:83], off sc1 nt
	v_pk_mul_f32 v[74:75], v[78:79], v[74:75]
	v_mul_f32_e32 v84, v165, v165
	v_mul_f32_e32 v82, 0xbfb8aa3b, v165
	v_pk_mul_f32 v[88:89], v[82:83], v[68:69] op_sel_hi:[0,1]
	v_pk_mul_f32 v[86:87], v[82:83], v[70:71] op_sel_hi:[0,1]
	v_exp_f32_e32 v83, v88
	v_exp_f32_e32 v86, v86
	v_exp_f32_e32 v87, v87
	v_pk_mul_f32 v[66:67], v[70:71], v[66:67]
	v_pk_mul_f32 v[76:77], v[82:83], v[76:77] op_sel_hi:[0,1]
	v_pk_mul_f32 v[78:79], v[82:83], v[78:79] op_sel_hi:[0,1]
	v_exp_f32_e32 v82, v76
	v_add_f32_e32 v76, 1.0, v83
	v_exp_f32_e32 v83, v89
	v_exp_f32_e32 v85, v77
	v_exp_f32_e32 v88, v79
	v_add_f32_e32 v79, 1.0, v87
	v_add_f32_e32 v77, 1.0, v83
	v_add_f32_e32 v83, 1.0, v85
	v_exp_f32_e32 v85, v78
	v_add_f32_e32 v78, 1.0, v86
	v_rcp_f32_e32 v76, v76
	v_add_f32_e32 v82, 1.0, v82
	v_rcp_f32_e32 v77, v77
	v_rcp_f32_e32 v78, v78
	v_add_f32_e32 v85, 1.0, v85
	v_rcp_f32_e32 v79, v79
	v_rcp_f32_e32 v82, v82
	v_rcp_f32_e32 v83, v83
	v_rcp_f32_e32 v86, v85
	v_add_f32_e32 v85, 1.0, v88
	v_rcp_f32_e32 v87, v85
	v_pk_mul_f32 v[64:65], v[68:69], v[64:65]
	v_pk_mul_f32 v[66:67], v[84:85], v[66:67] op_sel_hi:[0,1]
	v_pk_mul_f32 v[64:65], v[84:85], v[64:65] op_sel_hi:[0,1]
	v_lshl_add_u64 v[80:81], s[38:39], 0, v[142:143]
	v_pk_mul_f32 v[68:69], v[84:85], v[72:73] op_sel_hi:[0,1]
	v_pk_mul_f32 v[66:67], v[78:79], v[66:67]
	v_pk_mul_f32 v[64:65], v[76:77], v[64:65]
	v_lshl_add_u64 v[80:81], v[80:81], 0, v[208:209]
	v_pk_mul_f32 v[70:71], v[84:85], v[74:75] op_sel_hi:[0,1]
	v_pk_mul_f32 v[68:69], v[82:83], v[68:69]
	v_cvt_pk_bf16_f32 v64, v64, v65
	v_cvt_pk_bf16_f32 v65, v66, v67
	v_pk_mul_f32 v[70:71], v[86:87], v[70:71]
	v_cvt_pk_bf16_f32 v66, v68, v69
	v_pk_mul_f32 v[56:57], v[60:61], v[56:57]
	v_cvt_pk_bf16_f32 v67, v70, v71
	global_store_dwordx4 v[80:81], v[64:67], off sc1 nt
	v_pk_mul_f32 v[58:59], v[62:63], v[58:59]
	v_mul_f32_e32 v68, v164, v164
	v_mul_f32_e32 v66, 0xbfb8aa3b, v164
	v_pk_mul_f32 v[72:73], v[66:67], v[52:53] op_sel_hi:[0,1]
	v_pk_mul_f32 v[70:71], v[66:67], v[54:55] op_sel_hi:[0,1]
	v_exp_f32_e32 v67, v72
	v_exp_f32_e32 v70, v70
	v_exp_f32_e32 v71, v71
	v_pk_mul_f32 v[50:51], v[54:55], v[50:51]
	v_pk_mul_f32 v[60:61], v[66:67], v[60:61] op_sel_hi:[0,1]
	v_pk_mul_f32 v[62:63], v[66:67], v[62:63] op_sel_hi:[0,1]
	v_exp_f32_e32 v66, v60
	v_add_f32_e32 v60, 1.0, v67
	v_exp_f32_e32 v67, v73
	v_exp_f32_e32 v69, v61
	v_exp_f32_e32 v72, v63
	v_add_f32_e32 v63, 1.0, v71
	v_add_f32_e32 v61, 1.0, v67
	v_add_f32_e32 v67, 1.0, v69
	v_exp_f32_e32 v69, v62
	v_add_f32_e32 v62, 1.0, v70
	v_rcp_f32_e32 v60, v60
	v_add_f32_e32 v66, 1.0, v66
	v_rcp_f32_e32 v61, v61
	v_rcp_f32_e32 v62, v62
	v_add_f32_e32 v69, 1.0, v69
	v_rcp_f32_e32 v63, v63
	v_rcp_f32_e32 v66, v66
	v_rcp_f32_e32 v67, v67
	v_rcp_f32_e32 v70, v69
	v_add_f32_e32 v69, 1.0, v72
	v_rcp_f32_e32 v71, v69
	v_pk_mul_f32 v[48:49], v[52:53], v[48:49]
	v_pk_mul_f32 v[50:51], v[68:69], v[50:51] op_sel_hi:[0,1]
	v_pk_mul_f32 v[48:49], v[68:69], v[48:49] op_sel_hi:[0,1]
	v_lshl_add_u64 v[64:65], s[38:39], 0, v[144:145]
	v_pk_mul_f32 v[52:53], v[68:69], v[56:57] op_sel_hi:[0,1]
	v_pk_mul_f32 v[50:51], v[62:63], v[50:51]
	v_pk_mul_f32 v[48:49], v[60:61], v[48:49]
	v_lshl_add_u64 v[64:65], v[64:65], 0, v[208:209]
	v_pk_mul_f32 v[54:55], v[68:69], v[58:59] op_sel_hi:[0,1]
	v_pk_mul_f32 v[52:53], v[66:67], v[52:53]
	v_cvt_pk_bf16_f32 v48, v48, v49
	v_cvt_pk_bf16_f32 v49, v50, v51
	v_pk_mul_f32 v[54:55], v[70:71], v[54:55]
	v_cvt_pk_bf16_f32 v50, v52, v53
	v_pk_mul_f32 v[40:41], v[44:45], v[40:41]
	v_cvt_pk_bf16_f32 v51, v54, v55
	global_store_dwordx4 v[64:65], v[48:51], off sc1 nt
	v_pk_mul_f32 v[42:43], v[46:47], v[42:43]
	v_mul_f32_e32 v52, v163, v163
	v_mul_f32_e32 v50, 0xbfb8aa3b, v163
	v_pk_mul_f32 v[56:57], v[50:51], v[36:37] op_sel_hi:[0,1]
	v_pk_mul_f32 v[54:55], v[50:51], v[38:39] op_sel_hi:[0,1]
	v_exp_f32_e32 v51, v56
	v_exp_f32_e32 v54, v54
	v_exp_f32_e32 v55, v55
	v_pk_mul_f32 v[34:35], v[38:39], v[34:35]
	v_pk_mul_f32 v[44:45], v[50:51], v[44:45] op_sel_hi:[0,1]
	v_pk_mul_f32 v[46:47], v[50:51], v[46:47] op_sel_hi:[0,1]
	v_exp_f32_e32 v50, v44
	v_add_f32_e32 v44, 1.0, v51
	v_exp_f32_e32 v51, v57
	v_exp_f32_e32 v53, v45
	v_exp_f32_e32 v56, v47
	v_add_f32_e32 v47, 1.0, v55
	v_add_f32_e32 v45, 1.0, v51
	v_add_f32_e32 v51, 1.0, v53
	v_exp_f32_e32 v53, v46
	v_add_f32_e32 v46, 1.0, v54
	v_rcp_f32_e32 v44, v44
	v_add_f32_e32 v50, 1.0, v50
	v_rcp_f32_e32 v45, v45
	v_rcp_f32_e32 v46, v46
	v_add_f32_e32 v53, 1.0, v53
	v_rcp_f32_e32 v47, v47
	v_rcp_f32_e32 v50, v50
	v_rcp_f32_e32 v51, v51
	v_rcp_f32_e32 v54, v53
	v_add_f32_e32 v53, 1.0, v56
	v_rcp_f32_e32 v55, v53
	v_pk_mul_f32 v[32:33], v[36:37], v[32:33]
	v_pk_mul_f32 v[34:35], v[52:53], v[34:35] op_sel_hi:[0,1]
	v_pk_mul_f32 v[32:33], v[52:53], v[32:33] op_sel_hi:[0,1]
	v_lshl_add_u64 v[48:49], s[38:39], 0, v[146:147]
	v_pk_mul_f32 v[36:37], v[52:53], v[40:41] op_sel_hi:[0,1]
	v_pk_mul_f32 v[34:35], v[46:47], v[34:35]
	v_pk_mul_f32 v[32:33], v[44:45], v[32:33]
	v_lshl_add_u64 v[48:49], v[48:49], 0, v[208:209]
	v_pk_mul_f32 v[38:39], v[52:53], v[42:43] op_sel_hi:[0,1]
	v_pk_mul_f32 v[36:37], v[50:51], v[36:37]
	v_cvt_pk_bf16_f32 v32, v32, v33
	v_cvt_pk_bf16_f32 v33, v34, v35
	v_pk_mul_f32 v[38:39], v[54:55], v[38:39]
	v_cvt_pk_bf16_f32 v34, v36, v37
	v_pk_mul_f32 v[24:25], v[28:29], v[24:25]
	v_cvt_pk_bf16_f32 v35, v38, v39
	global_store_dwordx4 v[48:49], v[32:35], off sc1 nt
	v_pk_mul_f32 v[26:27], v[30:31], v[26:27]
	v_mul_f32_e32 v36, v162, v162
	v_mul_f32_e32 v34, 0xbfb8aa3b, v162
	v_pk_mul_f32 v[40:41], v[34:35], v[20:21] op_sel_hi:[0,1]
	v_pk_mul_f32 v[38:39], v[34:35], v[22:23] op_sel_hi:[0,1]
	v_exp_f32_e32 v35, v40
	v_exp_f32_e32 v38, v38
	v_exp_f32_e32 v39, v39
	v_pk_mul_f32 v[18:19], v[22:23], v[18:19]
	v_pk_mul_f32 v[28:29], v[34:35], v[28:29] op_sel_hi:[0,1]
	v_pk_mul_f32 v[30:31], v[34:35], v[30:31] op_sel_hi:[0,1]
	v_exp_f32_e32 v34, v28
	v_add_f32_e32 v28, 1.0, v35
	v_exp_f32_e32 v35, v41
	v_exp_f32_e32 v37, v29
	v_exp_f32_e32 v40, v31
	v_add_f32_e32 v31, 1.0, v39
	v_add_f32_e32 v29, 1.0, v35
	v_add_f32_e32 v35, 1.0, v37
	v_exp_f32_e32 v37, v30
	v_add_f32_e32 v30, 1.0, v38
	v_rcp_f32_e32 v28, v28
	v_add_f32_e32 v34, 1.0, v34
	v_rcp_f32_e32 v29, v29
	v_rcp_f32_e32 v30, v30
	v_add_f32_e32 v37, 1.0, v37
	v_rcp_f32_e32 v31, v31
	v_rcp_f32_e32 v34, v34
	v_rcp_f32_e32 v35, v35
	v_rcp_f32_e32 v38, v37
	v_add_f32_e32 v37, 1.0, v40
	v_rcp_f32_e32 v39, v37
	v_pk_mul_f32 v[16:17], v[20:21], v[16:17]
	v_pk_mul_f32 v[18:19], v[36:37], v[18:19] op_sel_hi:[0,1]
	v_pk_mul_f32 v[16:17], v[36:37], v[16:17] op_sel_hi:[0,1]
	v_lshl_add_u64 v[32:33], s[38:39], 0, v[148:149]
	v_pk_mul_f32 v[20:21], v[36:37], v[24:25] op_sel_hi:[0,1]
	v_pk_mul_f32 v[18:19], v[30:31], v[18:19]
	v_pk_mul_f32 v[16:17], v[28:29], v[16:17]
	v_lshl_add_u64 v[32:33], v[32:33], 0, v[208:209]
	v_pk_mul_f32 v[22:23], v[36:37], v[26:27] op_sel_hi:[0,1]
	v_pk_mul_f32 v[20:21], v[34:35], v[20:21]
	v_cvt_pk_bf16_f32 v16, v16, v17
	v_cvt_pk_bf16_f32 v17, v18, v19
	v_pk_mul_f32 v[22:23], v[38:39], v[22:23]
	v_cvt_pk_bf16_f32 v18, v20, v21
	v_pk_mul_f32 v[8:9], v[12:13], v[8:9]
	v_cvt_pk_bf16_f32 v19, v22, v23
	global_store_dwordx4 v[32:33], v[16:19], off sc1 nt
	v_pk_mul_f32 v[10:11], v[14:15], v[10:11]
	v_mul_f32_e32 v20, v161, v161
	v_mul_f32_e32 v18, 0xbfb8aa3b, v161
	v_pk_mul_f32 v[24:25], v[18:19], v[4:5] op_sel_hi:[0,1]
	v_pk_mul_f32 v[22:23], v[18:19], v[6:7] op_sel_hi:[0,1]
	v_exp_f32_e32 v19, v24
	v_exp_f32_e32 v22, v22
	v_exp_f32_e32 v23, v23
	v_pk_mul_f32 v[2:3], v[6:7], v[2:3]
	v_pk_mul_f32 v[12:13], v[18:19], v[12:13] op_sel_hi:[0,1]
	v_pk_mul_f32 v[14:15], v[18:19], v[14:15] op_sel_hi:[0,1]
	v_exp_f32_e32 v18, v12
	v_add_f32_e32 v12, 1.0, v19
	v_exp_f32_e32 v19, v25
	v_exp_f32_e32 v21, v13
	v_exp_f32_e32 v24, v15
	v_add_f32_e32 v15, 1.0, v23
	v_add_f32_e32 v13, 1.0, v19
	v_add_f32_e32 v19, 1.0, v21
	v_exp_f32_e32 v21, v14
	v_add_f32_e32 v14, 1.0, v22
	v_rcp_f32_e32 v12, v12
	v_add_f32_e32 v18, 1.0, v18
	v_add_f32_e32 v21, 1.0, v21
	v_rcp_f32_e32 v13, v13
	v_rcp_f32_e32 v14, v14
	v_rcp_f32_e32 v22, v21
	v_rcp_f32_e32 v15, v15
	v_add_f32_e32 v21, 1.0, v24
	v_rcp_f32_e32 v18, v18
	v_rcp_f32_e32 v19, v19
	v_rcp_f32_e32 v23, v21
	v_pk_mul_f32 v[0:1], v[4:5], v[0:1]
	v_lshl_add_u64 v[16:17], s[38:39], 0, v[150:151]
	v_pk_mul_f32 v[0:1], v[20:21], v[0:1] op_sel_hi:[0,1]
	v_pk_mul_f32 v[2:3], v[20:21], v[2:3] op_sel_hi:[0,1]
	v_lshl_add_u64 v[16:17], v[16:17], 0, v[208:209]
	v_pk_mul_f32 v[4:5], v[20:21], v[8:9] op_sel_hi:[0,1]
	v_pk_mul_f32 v[6:7], v[20:21], v[10:11] op_sel_hi:[0,1]
	v_pk_mul_f32 v[2:3], v[14:15], v[2:3]
	v_pk_mul_f32 v[0:1], v[12:13], v[0:1]
	s_andn2_b64 vcc, exec, s[36:37]
	s_mov_b64 s[2:3], -1
	v_pk_mul_f32 v[6:7], v[22:23], v[6:7]
	v_pk_mul_f32 v[4:5], v[18:19], v[4:5]
	v_cvt_pk_bf16_f32 v0, v0, v1
	v_cvt_pk_bf16_f32 v1, v2, v3
	s_nop 0
	v_cvt_pk_bf16_f32 v2, v4, v5
	v_cvt_pk_bf16_f32 v3, v6, v7
	global_store_dwordx4 v[16:17], v[0:3], off sc1 nt
	s_cbranch_vccnz .LBB0_567
	s_andn2_b64 vcc, exec, s[22:23]
	s_cbranch_vccnz .LBB0_566
	s_barrier
	s_branch .LBB0_566
